# A/B of the GEMM static priority raise: leading half (waves 0-3) instead of the trailing half (timing 1)
# speedup vs baseline: 1.0194x; 1.0026x over previous
.LBB0_18:
	s_add_u32 s14, s74, 0x23400000
	s_addc_u32 s15, s75, 0
	s_lshl_b32 s8, s8, 5
	s_and_b32 s8, s8, 0x60
	s_add_i32 m0, s31, 0x18000
	v_lshl_add_u64 v[6:7], v[6:7], 0, s[26:27]
	s_lshl_b32 s37, s13, 6
	s_lshl_b32 s13, s13, 13
	s_lshl_b32 s33, s8, 7
	s_waitcnt vmcnt(2)
	s_barrier
	global_load_lds_dwordx4 v[6:7], off
	v_lshl_add_u64 v[4:5], v[4:5], 0, s[26:27]
	s_add_i32 m0, s31, 0x1a000
	s_add_i32 s38, s31, 0x8000
	s_add_i32 s39, s31, 0xa000
	global_load_lds_dwordx4 v[4:5], off
	v_lshl_add_u64 v[0:1], v[0:1], 0, s[26:27]
	s_mov_b32 m0, s38
	s_add_u32 s20, s58, 0x80080
	global_load_lds_dwordx4 v[0:1], off
	v_lshl_add_u64 v[0:1], v[2:3], 0, s[26:27]
	s_mov_b32 m0, s39
	s_addc_u32 s21, s59, 0
	global_load_lds_dwordx4 v[0:1], off
	s_add_i32 m0, s31, 0x1c000
	v_lshl_add_u64 v[0:1], s[20:21], 0, v[184:185]
	global_load_lds_dwordx4 v[0:1], off
	v_lshl_add_u64 v[0:1], s[20:21], 0, v[128:129]
	s_add_i32 m0, s31, 0x1e000
	v_and_b32_e32 v140, 15, v8
	global_load_lds_dwordx4 v[0:1], off
	v_lshrrev_b32_e32 v0, 1, v8
	v_and_b32_e32 v0, 24, v0
	v_lshlrev_b32_e32 v1, 1, v0
	v_lshlrev_b32_e32 v2, 2, v8
	v_or_b32_e32 v142, s8, v0
	v_lshlrev_b32_e32 v0, 15, v13
	v_lshl_or_b32 v1, v140, 6, v1
	v_and_b32_e32 v2, 32, v2
	v_and_b32_e32 v0, 0xffff0000, v0
	v_bitop3_b32 v3, v1, s13, v2 bitop3:0xde
	v_bitop3_b32 v141, v1, s33, v2 bitop3:0xde
	v_lshl_add_u32 v0, v12, 12, v0
	v_and_b32_e32 v1, 1, v13
	v_lshl_or_b32 v0, v1, 6, v0
	v_lshl_add_u32 v134, v14, 1, v0
	v_lshlrev_b32_e32 v0, 15, v9
	v_and_b32_e32 v0, 0xffff0000, v0
	s_waitcnt vmcnt(6)
	v_lshl_add_u32 v0, v10, 12, v0
	v_and_b32_e32 v1, 1, v9
	s_cmpk_lt_u32 s12, 0x100
	v_lshl_or_b32 v0, v1, 6, v0
	v_readlane_b32 s12, v255, 7
	s_cselect_b64 s[42:43], -1, 0
	v_mov_b32_e32 v135, v185
	v_lshl_add_u32 v136, v11, 1, v0
	v_mov_b32_e32 v137, v185
	s_mov_b32 s48, 0
	v_add_u32_e32 v143, 0, v3
	v_readlane_b32 s49, v255, 6
	s_mov_b32 s50, s12
	s_barrier
	v_readlane_b32 s13, v255, 8
	v_and_b32_e32 v246, 15, v203
	v_bfe_u32 v247, v203, 4, 2
	v_lshrrev_b32_e32 v248, 1, v246
	v_xor_b32_e32 v249, v247, v248
	v_lshlrev_b32_e32 v249, 4, v249
	v_lshrrev_b32_e32 v250, 3, v246
	v_lshlrev_b32_e32 v250, 10, v250
	v_and_b32_e32 v251, 7, v246
	v_lshl_add_u32 v250, v251, 7, v250
	v_add_u32_e32 v250, v250, v249
	v_lshrrev_b32_e32 v251, 8, v203
	v_lshl_add_u32 v143, v251, 13, v250
	v_xor_b32_e32 v240, 64, v143
	v_bfe_u32 v251, v203, 6, 2
	v_lshl_add_u32 v141, v251, 12, v250
	v_xor_b32_e32 v241, 64, v141
	v_mov_b32_e32 v134, v132
	v_mov_b32_e32 v136, v130
	v_readfirstlane_b32 s98, v203
	s_nop 3
	s_lshr_b32 s98, s98, 8
	s_cmp_eq_u32 s98, 0
	s_cbranch_scc0 .Lgp_21
	s_setprio 1

.LBB0_176:
	s_add_u32 s56, s74, 0x23400000
	s_addc_u32 s57, s75, 0
	s_add_u32 s58, s74, 0xac00000
	s_addc_u32 s59, s75, 0
	s_add_u32 s60, s74, 0xad80000
	s_addc_u32 s61, s75, 0
	s_and_b32 s71, s8, 3
	s_add_i32 m0, s30, 0x18000
	v_lshl_add_u64 v[6:7], v[6:7], 0, s[26:27]
	s_lshl_b32 s96, s7, 6
	s_lshl_b32 s7, s7, 13
	s_lshl_b32 s12, s71, 12
	s_waitcnt vmcnt(2)
	s_barrier
	global_load_lds_dwordx4 v[6:7], off
	v_lshl_add_u64 v[4:5], v[4:5], 0, s[26:27]
	s_add_i32 m0, s30, 0x1a000
	s_add_i32 s34, s30, 0x8000
	s_add_i32 s35, s30, 0xa000
	global_load_lds_dwordx4 v[4:5], off
	v_lshl_add_u64 v[0:1], v[0:1], 0, s[26:27]
	s_mov_b32 m0, s34
	s_add_u32 s8, s44, 0x80080
	global_load_lds_dwordx4 v[0:1], off
	v_lshl_add_u64 v[0:1], v[2:3], 0, s[26:27]
	s_mov_b32 m0, s35
	s_addc_u32 s9, s45, 0
	global_load_lds_dwordx4 v[0:1], off
	s_add_i32 m0, s30, 0x1c000
	v_lshl_add_u64 v[0:1], s[8:9], 0, v[184:185]
	global_load_lds_dwordx4 v[0:1], off
	v_lshl_add_u64 v[0:1], s[8:9], 0, v[128:129]
	s_add_i32 m0, s30, 0x1e000
	v_and_b32_e32 v146, 15, v8
	global_load_lds_dwordx4 v[0:1], off
	v_bfe_u32 v0, v8, 4, 2
	v_lshlrev_b32_e32 v1, 3, v0
	v_lshlrev_b32_e32 v2, 4, v0
	v_cmp_eq_u32_e64 s[40:41], 0, v0
	v_lshlrev_b32_e32 v0, 15, v13
	v_and_b32_e32 v0, 0xffff0000, v0
	v_lshl_or_b32 v148, s71, 5, v1
	v_lshl_add_u32 v0, v12, 12, v0
	v_and_b32_e32 v1, 1, v13
	v_lshl_or_b32 v0, v1, 6, v0
	v_lshl_add_u32 v134, v14, 1, v0
	v_lshlrev_b32_e32 v0, 15, v9
	v_lshlrev_b32_e32 v3, 2, v8
	v_and_b32_e32 v0, 0xffff0000, v0
	v_lshl_or_b32 v2, v146, 6, v2
	v_and_b32_e32 v3, 32, v3
	s_waitcnt vmcnt(6)
	v_lshl_add_u32 v0, v10, 12, v0
	v_and_b32_e32 v1, 1, v9
	v_bitop3_b32 v4, v2, s7, v3 bitop3:0xde
	s_cmpk_lt_u32 s6, 0x100
	v_lshl_or_b32 v0, v1, 6, v0
	v_readlane_b32 s6, v255, 40
	v_bitop3_b32 v147, v2, s12, v3 bitop3:0xde
	s_cselect_b64 s[62:63], -1, 0
	s_mov_b32 s36, 0
	v_mov_b32_e32 v135, v185
	v_lshl_add_u32 v136, v11, 1, v0
	v_mov_b32_e32 v137, v185
	v_add_u32_e32 v149, 0, v4
	v_readlane_b32 s9, v255, 26
	s_mov_b32 s16, s6
	s_barrier
	v_readlane_b32 s7, v255, 41
	v_and_b32_e32 v246, 15, v203
	v_bfe_u32 v247, v203, 4, 2
	v_lshrrev_b32_e32 v248, 1, v246
	v_xor_b32_e32 v249, v247, v248
	v_lshlrev_b32_e32 v249, 4, v249
	v_lshrrev_b32_e32 v250, 3, v246
	v_lshlrev_b32_e32 v250, 10, v250
	v_and_b32_e32 v251, 7, v246
	v_lshl_add_u32 v250, v251, 7, v250
	v_add_u32_e32 v250, v250, v249
	v_lshrrev_b32_e32 v251, 8, v203
	v_lshl_add_u32 v149, v251, 13, v250
	v_xor_b32_e32 v240, 64, v149
	v_bfe_u32 v251, v203, 6, 2
	v_lshl_add_u32 v147, v251, 12, v250
	v_xor_b32_e32 v241, 64, v147
	v_mov_b32_e32 v134, v132
	v_mov_b32_e32 v136, v130
	v_readfirstlane_b32 s98, v203
	s_nop 3
	s_lshr_b32 s98, s98, 8
	s_cmp_eq_u32 s98, 0
	s_cbranch_scc0 .Lgp_179
	s_setprio 1
